# EpiIn log-decay tile (pn 9): logsigmoid blocks hand-written with packed f32 ops, dead denormal/inf branches of log removed, b_alpha loaded once per tile
# speedup vs baseline: 1.0379x; 1.0038x over previous
.LBB0_150:
	s_lshl_b32 s8, s35, 8
	s_add_i32 s8, s8, s47
	s_and_b32 s9, s54, -2
	s_cmp_eq_u32 s9, 4
	s_cselect_b64 s[10:11], -1, 0
	s_lshl_b32 s9, s34, 10
	v_mov_b32_e32 v132, v3
	v_mov_b32_e32 v133, v157
	s_add_i32 s9, s51, s9
	s_mov_b32 s23, 0xbfb8aa3b
	v_lshl_add_u32 v176, v132, 2, s9
	ds_read_b32 v170, v176
	v_add_u32_e32 v152, s8, v132
	v_ashrrev_i32_e32 v153, 31, v152
	s_mov_b32 s25, 0x3f317217
	s_mov_b32 s55, 0x7f800000
	s_mov_b32 s57, 0x42fc0000
	s_mov_b32 s56, 0x3e000000
	v_lshl_add_u32 v150, v133, 3, s48
	v_lshlrev_b64 v[154:155], 9, v[152:153]
	s_waitcnt lgkmcnt(0)
	v_pk_mul_f32 v[130:131], v[130:131], v[170:171] op_sel_hi:[1,0]
	v_pk_mul_f32 v[128:129], v[128:129], v[170:171] op_sel_hi:[1,0]
	v_pk_mul_f32 v[126:127], v[126:127], v[170:171] op_sel_hi:[1,0]
	v_pk_mul_f32 v[124:125], v[124:125], v[170:171] op_sel_hi:[1,0]
	s_mov_b64 s[34:35], -1
	s_mov_b64 s[30:31], 0
	s_cmp_lt_i32 s54, 9
	s_mov_b64 s[8:9], 0
	s_cbranch_scc1 .LBB0_154
	s_cmp_eq_u32 s54, 9
	s_mov_b64 s[8:9], -1
	s_cbranch_scc0 .LBB0_153
	v_ashrrev_i32_e32 v151, 31, v150
	v_lshl_add_u64 v[184:185], v[150:151], 2, s[18:19]
	global_load_dwordx4 v[192:195], v[184:185], off
	global_load_dwordx4 v[196:199], v[184:185], off offset:16
	global_load_dwordx4 v[200:203], v[184:185], off offset:512
	global_load_dwordx4 v[204:207], v[184:185], off offset:528
	v_mov_b32_e32 v228, 1.0
	v_mov_b32_e32 v229, 1.0
	v_mov_b32_e32 v230, 0x3f317217
	v_mov_b32_e32 v231, 0x3f317217
	v_mov_b32_e32 v232, 0x3377d1cf
	v_mov_b32_e32 v233, 0x3377d1cf
	v_mov_b32_e32 v234, 0x3d800000
	v_mov_b32_e32 v235, 0x3d800000
	s_waitcnt vmcnt(0)
	v_pk_add_f32 v[128:129], v[128:129], v[192:193]
	v_pk_add_f32 v[130:131], v[130:131], v[194:195]
	v_pk_add_f32 v[124:125], v[124:125], v[196:197]
	v_pk_add_f32 v[126:127], v[126:127], v[198:199]
	v_mul_f32_e64 v184, |v128|, s23
	v_mul_f32_e64 v185, |v129|, s23
	v_mul_f32_e64 v186, |v130|, s23
	v_mul_f32_e64 v187, |v131|, s23
	v_mul_f32_e64 v188, |v124|, s23
	v_mul_f32_e64 v189, |v125|, s23
	v_mul_f32_e64 v190, |v126|, s23
	v_mul_f32_e64 v191, |v127|, s23
	v_min_f32_e32 v128, 0, v128
	v_min_f32_e32 v129, 0, v129
	v_min_f32_e32 v130, 0, v130
	v_min_f32_e32 v131, 0, v131
	v_min_f32_e32 v124, 0, v124
	v_min_f32_e32 v125, 0, v125
	v_min_f32_e32 v126, 0, v126
	v_min_f32_e32 v127, 0, v127
	v_exp_f32_e32 v184, v184
	v_exp_f32_e32 v185, v185
	v_exp_f32_e32 v186, v186
	v_exp_f32_e32 v187, v187
	v_exp_f32_e32 v188, v188
	v_exp_f32_e32 v189, v189
	v_exp_f32_e32 v190, v190
	v_exp_f32_e32 v191, v191
	v_pk_add_f32 v[184:185], v[184:185], v[228:229]
	v_pk_add_f32 v[186:187], v[186:187], v[228:229]
	v_pk_add_f32 v[188:189], v[188:189], v[228:229]
	v_pk_add_f32 v[190:191], v[190:191], v[228:229]
	v_log_f32_e32 v184, v184
	v_log_f32_e32 v185, v185
	v_log_f32_e32 v186, v186
	v_log_f32_e32 v187, v187
	v_log_f32_e32 v188, v188
	v_log_f32_e32 v189, v189
	v_log_f32_e32 v190, v190
	v_log_f32_e32 v191, v191
	v_pk_mul_f32 v[220:221], v[230:231], v[184:185]
	v_pk_mul_f32 v[222:223], v[230:231], v[186:187]
	v_pk_mul_f32 v[224:225], v[230:231], v[188:189]
	v_pk_mul_f32 v[226:227], v[230:231], v[190:191]
	v_pk_fma_f32 v[220:221], v[184:185], v[230:231], v[220:221] neg_lo:[0,0,1] neg_hi:[0,0,1]
	v_pk_fma_f32 v[222:223], v[186:187], v[230:231], v[222:223] neg_lo:[0,0,1] neg_hi:[0,0,1]
	v_pk_fma_f32 v[224:225], v[188:189], v[230:231], v[224:225] neg_lo:[0,0,1] neg_hi:[0,0,1]
	v_pk_fma_f32 v[226:227], v[190:191], v[230:231], v[226:227] neg_lo:[0,0,1] neg_hi:[0,0,1]
	v_pk_fma_f32 v[220:221], v[232:233], v[184:185], v[220:221]
	v_pk_fma_f32 v[222:223], v[232:233], v[186:187], v[222:223]
	v_pk_fma_f32 v[224:225], v[232:233], v[188:189], v[224:225]
	v_pk_fma_f32 v[226:227], v[232:233], v[190:191], v[226:227]
	v_pk_fma_f32 v[220:221], v[230:231], v[184:185], v[220:221]
	v_pk_fma_f32 v[222:223], v[230:231], v[186:187], v[222:223]
	v_pk_fma_f32 v[224:225], v[230:231], v[188:189], v[224:225]
	v_pk_fma_f32 v[226:227], v[230:231], v[190:191], v[226:227]
	v_pk_add_f32 v[128:129], v[128:129], v[220:221] neg_lo:[0,1] neg_hi:[0,1]
	v_pk_add_f32 v[130:131], v[130:131], v[222:223] neg_lo:[0,1] neg_hi:[0,1]
	v_pk_add_f32 v[124:125], v[124:125], v[224:225] neg_lo:[0,1] neg_hi:[0,1]
	v_pk_add_f32 v[126:127], v[126:127], v[226:227] neg_lo:[0,1] neg_hi:[0,1]
	v_pk_mul_f32 v[128:129], v[234:235], v[128:129]
	v_pk_mul_f32 v[130:131], v[234:235], v[130:131]
	v_pk_mul_f32 v[124:125], v[234:235], v[124:125]
	v_pk_mul_f32 v[126:127], v[234:235], v[126:127]
	v_cvt_pk_bf16_f32 v134, v128, v129
	v_cvt_pk_bf16_f32 v135, v130, v131
	v_cvt_pk_bf16_f32 v136, v124, v125
	v_cvt_pk_bf16_f32 v137, v126, v127
	v_lshl_add_u64 v[132:133], s[16:17], 0, v[154:155]
	v_lshl_add_u64 v[132:133], v[150:151], 1, v[132:133]
	global_store_dwordx4 v[132:133], v[134:137], off
	s_mov_b64 s[8:9], 0

.LBB0_164:
	v_mov_b32_e32 v171, v170
	s_nop 0
	v_mov_b32_e32 v124, v170
	v_mov_b32_e32 v125, v170
	v_pk_mul_f32 v[122:123], v[122:123], v[124:125]
	v_pk_mul_f32 v[120:121], v[120:121], v[170:171]
	v_pk_mul_f32 v[118:119], v[118:119], v[124:125]
	v_pk_mul_f32 v[116:117], v[116:117], v[170:171]
	s_mov_b64 s[36:37], -1
	s_mov_b64 s[34:35], 0
	s_cmp_lt_i32 s54, 9
	s_mov_b64 s[10:11], 0
	s_cbranch_scc1 .LBB0_168
	s_cmp_eq_u32 s54, 9
	s_mov_b64 s[10:11], -1
	s_cbranch_scc0 .LBB0_167
	v_pk_add_f32 v[120:121], v[120:121], v[200:201]
	v_pk_add_f32 v[122:123], v[122:123], v[202:203]
	v_pk_add_f32 v[116:117], v[116:117], v[204:205]
	v_pk_add_f32 v[118:119], v[118:119], v[206:207]
	v_mul_f32_e64 v184, |v120|, s23
	v_mul_f32_e64 v185, |v121|, s23
	v_mul_f32_e64 v186, |v122|, s23
	v_mul_f32_e64 v187, |v123|, s23
	v_mul_f32_e64 v188, |v116|, s23
	v_mul_f32_e64 v189, |v117|, s23
	v_mul_f32_e64 v190, |v118|, s23
	v_mul_f32_e64 v191, |v119|, s23
	v_min_f32_e32 v120, 0, v120
	v_min_f32_e32 v121, 0, v121
	v_min_f32_e32 v122, 0, v122
	v_min_f32_e32 v123, 0, v123
	v_min_f32_e32 v116, 0, v116
	v_min_f32_e32 v117, 0, v117
	v_min_f32_e32 v118, 0, v118
	v_min_f32_e32 v119, 0, v119
	v_exp_f32_e32 v184, v184
	v_exp_f32_e32 v185, v185
	v_exp_f32_e32 v186, v186
	v_exp_f32_e32 v187, v187
	v_exp_f32_e32 v188, v188
	v_exp_f32_e32 v189, v189
	v_exp_f32_e32 v190, v190
	v_exp_f32_e32 v191, v191
	v_pk_add_f32 v[184:185], v[184:185], v[228:229]
	v_pk_add_f32 v[186:187], v[186:187], v[228:229]
	v_pk_add_f32 v[188:189], v[188:189], v[228:229]
	v_pk_add_f32 v[190:191], v[190:191], v[228:229]
	v_log_f32_e32 v184, v184
	v_log_f32_e32 v185, v185
	v_log_f32_e32 v186, v186
	v_log_f32_e32 v187, v187
	v_log_f32_e32 v188, v188
	v_log_f32_e32 v189, v189
	v_log_f32_e32 v190, v190
	v_log_f32_e32 v191, v191
	v_pk_mul_f32 v[220:221], v[230:231], v[184:185]
	v_pk_mul_f32 v[222:223], v[230:231], v[186:187]
	v_pk_mul_f32 v[224:225], v[230:231], v[188:189]
	v_pk_mul_f32 v[226:227], v[230:231], v[190:191]
	v_pk_fma_f32 v[220:221], v[184:185], v[230:231], v[220:221] neg_lo:[0,0,1] neg_hi:[0,0,1]
	v_pk_fma_f32 v[222:223], v[186:187], v[230:231], v[222:223] neg_lo:[0,0,1] neg_hi:[0,0,1]
	v_pk_fma_f32 v[224:225], v[188:189], v[230:231], v[224:225] neg_lo:[0,0,1] neg_hi:[0,0,1]
	v_pk_fma_f32 v[226:227], v[190:191], v[230:231], v[226:227] neg_lo:[0,0,1] neg_hi:[0,0,1]
	v_pk_fma_f32 v[220:221], v[232:233], v[184:185], v[220:221]
	v_pk_fma_f32 v[222:223], v[232:233], v[186:187], v[222:223]
	v_pk_fma_f32 v[224:225], v[232:233], v[188:189], v[224:225]
	v_pk_fma_f32 v[226:227], v[232:233], v[190:191], v[226:227]
	v_pk_fma_f32 v[220:221], v[230:231], v[184:185], v[220:221]
	v_pk_fma_f32 v[222:223], v[230:231], v[186:187], v[222:223]
	v_pk_fma_f32 v[224:225], v[230:231], v[188:189], v[224:225]
	v_pk_fma_f32 v[226:227], v[230:231], v[190:191], v[226:227]
	v_pk_add_f32 v[120:121], v[120:121], v[220:221] neg_lo:[0,1] neg_hi:[0,1]
	v_pk_add_f32 v[122:123], v[122:123], v[222:223] neg_lo:[0,1] neg_hi:[0,1]
	v_pk_add_f32 v[116:117], v[116:117], v[224:225] neg_lo:[0,1] neg_hi:[0,1]
	v_pk_add_f32 v[118:119], v[118:119], v[226:227] neg_lo:[0,1] neg_hi:[0,1]
	v_pk_mul_f32 v[120:121], v[234:235], v[120:121]
	v_pk_mul_f32 v[122:123], v[234:235], v[122:123]
	v_pk_mul_f32 v[116:117], v[234:235], v[116:117]
	v_pk_mul_f32 v[118:119], v[234:235], v[118:119]
	v_cvt_pk_bf16_f32 v126, v120, v121
	v_cvt_pk_bf16_f32 v127, v122, v123
	v_cvt_pk_bf16_f32 v128, v116, v117
	v_cvt_pk_bf16_f32 v129, v118, v119
	v_lshl_add_u64 v[124:125], s[16:17], 0, v[154:155]
	v_lshl_add_u64 v[124:125], v[150:151], 1, v[124:125]
	global_store_dwordx4 v[124:125], v[126:129], off offset:256
	s_mov_b64 s[10:11], 0

.LBB0_176:
	ds_read_b32 v126, v176 offset:64
	v_add_u32_e32 v128, 16, v152
	v_ashrrev_i32_e32 v129, 31, v128
	v_lshlrev_b64 v[124:125], 9, v[128:129]
	s_mov_b64 s[36:37], -1
	s_waitcnt lgkmcnt(0)
	v_pk_mul_f32 v[114:115], v[114:115], v[126:127] op_sel_hi:[1,0]
	v_pk_mul_f32 v[112:113], v[112:113], v[126:127] op_sel_hi:[1,0]
	v_pk_mul_f32 v[110:111], v[110:111], v[126:127] op_sel_hi:[1,0]
	v_pk_mul_f32 v[108:109], v[108:109], v[126:127] op_sel_hi:[1,0]
	s_mov_b64 s[34:35], 0
	s_cmp_lt_i32 s54, 9
	s_mov_b64 s[10:11], 0
	s_cbranch_scc1 .LBB0_182
	s_cmp_eq_u32 s54, 9
	s_mov_b64 s[10:11], -1
	s_cbranch_scc0 .LBB0_179
	v_pk_add_f32 v[112:113], v[112:113], v[192:193]
	v_pk_add_f32 v[114:115], v[114:115], v[194:195]
	v_pk_add_f32 v[108:109], v[108:109], v[196:197]
	v_pk_add_f32 v[110:111], v[110:111], v[198:199]
	v_mul_f32_e64 v184, |v112|, s23
	v_mul_f32_e64 v185, |v113|, s23
	v_mul_f32_e64 v186, |v114|, s23
	v_mul_f32_e64 v187, |v115|, s23
	v_mul_f32_e64 v188, |v108|, s23
	v_mul_f32_e64 v189, |v109|, s23
	v_mul_f32_e64 v190, |v110|, s23
	v_mul_f32_e64 v191, |v111|, s23
	v_min_f32_e32 v112, 0, v112
	v_min_f32_e32 v113, 0, v113
	v_min_f32_e32 v114, 0, v114
	v_min_f32_e32 v115, 0, v115
	v_min_f32_e32 v108, 0, v108
	v_min_f32_e32 v109, 0, v109
	v_min_f32_e32 v110, 0, v110
	v_min_f32_e32 v111, 0, v111
	v_exp_f32_e32 v184, v184
	v_exp_f32_e32 v185, v185
	v_exp_f32_e32 v186, v186
	v_exp_f32_e32 v187, v187
	v_exp_f32_e32 v188, v188
	v_exp_f32_e32 v189, v189
	v_exp_f32_e32 v190, v190
	v_exp_f32_e32 v191, v191
	v_pk_add_f32 v[184:185], v[184:185], v[228:229]
	v_pk_add_f32 v[186:187], v[186:187], v[228:229]
	v_pk_add_f32 v[188:189], v[188:189], v[228:229]
	v_pk_add_f32 v[190:191], v[190:191], v[228:229]
	v_log_f32_e32 v184, v184
	v_log_f32_e32 v185, v185
	v_log_f32_e32 v186, v186
	v_log_f32_e32 v187, v187
	v_log_f32_e32 v188, v188
	v_log_f32_e32 v189, v189
	v_log_f32_e32 v190, v190
	v_log_f32_e32 v191, v191
	v_pk_mul_f32 v[220:221], v[230:231], v[184:185]
	v_pk_mul_f32 v[222:223], v[230:231], v[186:187]
	v_pk_mul_f32 v[224:225], v[230:231], v[188:189]
	v_pk_mul_f32 v[226:227], v[230:231], v[190:191]
	v_pk_fma_f32 v[220:221], v[184:185], v[230:231], v[220:221] neg_lo:[0,0,1] neg_hi:[0,0,1]
	v_pk_fma_f32 v[222:223], v[186:187], v[230:231], v[222:223] neg_lo:[0,0,1] neg_hi:[0,0,1]
	v_pk_fma_f32 v[224:225], v[188:189], v[230:231], v[224:225] neg_lo:[0,0,1] neg_hi:[0,0,1]
	v_pk_fma_f32 v[226:227], v[190:191], v[230:231], v[226:227] neg_lo:[0,0,1] neg_hi:[0,0,1]
	v_pk_fma_f32 v[220:221], v[232:233], v[184:185], v[220:221]
	v_pk_fma_f32 v[222:223], v[232:233], v[186:187], v[222:223]
	v_pk_fma_f32 v[224:225], v[232:233], v[188:189], v[224:225]
	v_pk_fma_f32 v[226:227], v[232:233], v[190:191], v[226:227]
	v_pk_fma_f32 v[220:221], v[230:231], v[184:185], v[220:221]
	v_pk_fma_f32 v[222:223], v[230:231], v[186:187], v[222:223]
	v_pk_fma_f32 v[224:225], v[230:231], v[188:189], v[224:225]
	v_pk_fma_f32 v[226:227], v[230:231], v[190:191], v[226:227]
	v_pk_add_f32 v[112:113], v[112:113], v[220:221] neg_lo:[0,1] neg_hi:[0,1]
	v_pk_add_f32 v[114:115], v[114:115], v[222:223] neg_lo:[0,1] neg_hi:[0,1]
	v_pk_add_f32 v[108:109], v[108:109], v[224:225] neg_lo:[0,1] neg_hi:[0,1]
	v_pk_add_f32 v[110:111], v[110:111], v[226:227] neg_lo:[0,1] neg_hi:[0,1]
	v_pk_mul_f32 v[112:113], v[234:235], v[112:113]
	v_pk_mul_f32 v[114:115], v[234:235], v[114:115]
	v_pk_mul_f32 v[108:109], v[234:235], v[108:109]
	v_pk_mul_f32 v[110:111], v[234:235], v[110:111]
	v_cvt_pk_bf16_f32 v118, v112, v113
	v_cvt_pk_bf16_f32 v119, v114, v115
	v_cvt_pk_bf16_f32 v120, v108, v109
	v_cvt_pk_bf16_f32 v121, v110, v111
	v_lshl_add_u64 v[116:117], s[16:17], 0, v[124:125]
	v_lshl_add_u64 v[116:117], v[150:151], 1, v[116:117]
	global_store_dwordx4 v[116:117], v[118:121], off
	s_mov_b64 s[10:11], 0

.LBB0_192:
	v_mov_b32_e32 v127, v126
	s_nop 0
	v_mov_b32_e32 v108, v126
	v_mov_b32_e32 v109, v126
	v_pk_mul_f32 v[106:107], v[106:107], v[108:109]
	v_pk_mul_f32 v[104:105], v[104:105], v[126:127]
	v_pk_mul_f32 v[102:103], v[102:103], v[108:109]
	v_pk_mul_f32 v[100:101], v[100:101], v[126:127]
	s_mov_b64 s[36:37], -1
	s_mov_b64 s[34:35], 0
	s_cmp_lt_i32 s54, 9
	s_mov_b64 s[10:11], 0
	s_cbranch_scc1 .LBB0_196
	s_cmp_eq_u32 s54, 9
	s_mov_b64 s[10:11], -1
	s_cbranch_scc0 .LBB0_195
	v_pk_add_f32 v[104:105], v[104:105], v[200:201]
	v_pk_add_f32 v[106:107], v[106:107], v[202:203]
	v_pk_add_f32 v[100:101], v[100:101], v[204:205]
	v_pk_add_f32 v[102:103], v[102:103], v[206:207]
	v_mul_f32_e64 v184, |v104|, s23
	v_mul_f32_e64 v185, |v105|, s23
	v_mul_f32_e64 v186, |v106|, s23
	v_mul_f32_e64 v187, |v107|, s23
	v_mul_f32_e64 v188, |v100|, s23
	v_mul_f32_e64 v189, |v101|, s23
	v_mul_f32_e64 v190, |v102|, s23
	v_mul_f32_e64 v191, |v103|, s23
	v_min_f32_e32 v104, 0, v104
	v_min_f32_e32 v105, 0, v105
	v_min_f32_e32 v106, 0, v106
	v_min_f32_e32 v107, 0, v107
	v_min_f32_e32 v100, 0, v100
	v_min_f32_e32 v101, 0, v101
	v_min_f32_e32 v102, 0, v102
	v_min_f32_e32 v103, 0, v103
	v_exp_f32_e32 v184, v184
	v_exp_f32_e32 v185, v185
	v_exp_f32_e32 v186, v186
	v_exp_f32_e32 v187, v187
	v_exp_f32_e32 v188, v188
	v_exp_f32_e32 v189, v189
	v_exp_f32_e32 v190, v190
	v_exp_f32_e32 v191, v191
	v_pk_add_f32 v[184:185], v[184:185], v[228:229]
	v_pk_add_f32 v[186:187], v[186:187], v[228:229]
	v_pk_add_f32 v[188:189], v[188:189], v[228:229]
	v_pk_add_f32 v[190:191], v[190:191], v[228:229]
	v_log_f32_e32 v184, v184
	v_log_f32_e32 v185, v185
	v_log_f32_e32 v186, v186
	v_log_f32_e32 v187, v187
	v_log_f32_e32 v188, v188
	v_log_f32_e32 v189, v189
	v_log_f32_e32 v190, v190
	v_log_f32_e32 v191, v191
	v_pk_mul_f32 v[220:221], v[230:231], v[184:185]
	v_pk_mul_f32 v[222:223], v[230:231], v[186:187]
	v_pk_mul_f32 v[224:225], v[230:231], v[188:189]
	v_pk_mul_f32 v[226:227], v[230:231], v[190:191]
	v_pk_fma_f32 v[220:221], v[184:185], v[230:231], v[220:221] neg_lo:[0,0,1] neg_hi:[0,0,1]
	v_pk_fma_f32 v[222:223], v[186:187], v[230:231], v[222:223] neg_lo:[0,0,1] neg_hi:[0,0,1]
	v_pk_fma_f32 v[224:225], v[188:189], v[230:231], v[224:225] neg_lo:[0,0,1] neg_hi:[0,0,1]
	v_pk_fma_f32 v[226:227], v[190:191], v[230:231], v[226:227] neg_lo:[0,0,1] neg_hi:[0,0,1]
	v_pk_fma_f32 v[220:221], v[232:233], v[184:185], v[220:221]
	v_pk_fma_f32 v[222:223], v[232:233], v[186:187], v[222:223]
	v_pk_fma_f32 v[224:225], v[232:233], v[188:189], v[224:225]
	v_pk_fma_f32 v[226:227], v[232:233], v[190:191], v[226:227]
	v_pk_fma_f32 v[220:221], v[230:231], v[184:185], v[220:221]
	v_pk_fma_f32 v[222:223], v[230:231], v[186:187], v[222:223]
	v_pk_fma_f32 v[224:225], v[230:231], v[188:189], v[224:225]
	v_pk_fma_f32 v[226:227], v[230:231], v[190:191], v[226:227]
	v_pk_add_f32 v[104:105], v[104:105], v[220:221] neg_lo:[0,1] neg_hi:[0,1]
	v_pk_add_f32 v[106:107], v[106:107], v[222:223] neg_lo:[0,1] neg_hi:[0,1]
	v_pk_add_f32 v[100:101], v[100:101], v[224:225] neg_lo:[0,1] neg_hi:[0,1]
	v_pk_add_f32 v[102:103], v[102:103], v[226:227] neg_lo:[0,1] neg_hi:[0,1]
	v_pk_mul_f32 v[104:105], v[234:235], v[104:105]
	v_pk_mul_f32 v[106:107], v[234:235], v[106:107]
	v_pk_mul_f32 v[100:101], v[234:235], v[100:101]
	v_pk_mul_f32 v[102:103], v[234:235], v[102:103]
	v_cvt_pk_bf16_f32 v110, v104, v105
	v_cvt_pk_bf16_f32 v111, v106, v107
	v_cvt_pk_bf16_f32 v112, v100, v101
	v_cvt_pk_bf16_f32 v113, v102, v103
	v_lshl_add_u64 v[108:109], s[16:17], 0, v[124:125]
	v_lshl_add_u64 v[108:109], v[150:151], 1, v[108:109]
	global_store_dwordx4 v[108:109], v[110:113], off offset:256
	s_mov_b64 s[10:11], 0

.LBB0_204:
	ds_read_b32 v110, v176 offset:128
	v_add_u32_e32 v112, 32, v152
	v_ashrrev_i32_e32 v113, 31, v112
	v_lshlrev_b64 v[108:109], 9, v[112:113]
	s_mov_b64 s[36:37], -1
	s_waitcnt lgkmcnt(0)
	v_pk_mul_f32 v[98:99], v[98:99], v[110:111] op_sel_hi:[1,0]
	v_pk_mul_f32 v[96:97], v[96:97], v[110:111] op_sel_hi:[1,0]
	v_pk_mul_f32 v[94:95], v[94:95], v[110:111] op_sel_hi:[1,0]
	v_pk_mul_f32 v[92:93], v[92:93], v[110:111] op_sel_hi:[1,0]
	s_mov_b64 s[34:35], 0
	s_cmp_lt_i32 s54, 9
	s_mov_b64 s[10:11], 0
	s_cbranch_scc1 .LBB0_210
	s_cmp_eq_u32 s54, 9
	s_mov_b64 s[10:11], -1
	s_cbranch_scc0 .LBB0_207
	v_pk_add_f32 v[96:97], v[96:97], v[192:193]
	v_pk_add_f32 v[98:99], v[98:99], v[194:195]
	v_pk_add_f32 v[92:93], v[92:93], v[196:197]
	v_pk_add_f32 v[94:95], v[94:95], v[198:199]
	v_mul_f32_e64 v184, |v96|, s23
	v_mul_f32_e64 v185, |v97|, s23
	v_mul_f32_e64 v186, |v98|, s23
	v_mul_f32_e64 v187, |v99|, s23
	v_mul_f32_e64 v188, |v92|, s23
	v_mul_f32_e64 v189, |v93|, s23
	v_mul_f32_e64 v190, |v94|, s23
	v_mul_f32_e64 v191, |v95|, s23
	v_min_f32_e32 v96, 0, v96
	v_min_f32_e32 v97, 0, v97
	v_min_f32_e32 v98, 0, v98
	v_min_f32_e32 v99, 0, v99
	v_min_f32_e32 v92, 0, v92
	v_min_f32_e32 v93, 0, v93
	v_min_f32_e32 v94, 0, v94
	v_min_f32_e32 v95, 0, v95
	v_exp_f32_e32 v184, v184
	v_exp_f32_e32 v185, v185
	v_exp_f32_e32 v186, v186
	v_exp_f32_e32 v187, v187
	v_exp_f32_e32 v188, v188
	v_exp_f32_e32 v189, v189
	v_exp_f32_e32 v190, v190
	v_exp_f32_e32 v191, v191
	v_pk_add_f32 v[184:185], v[184:185], v[228:229]
	v_pk_add_f32 v[186:187], v[186:187], v[228:229]
	v_pk_add_f32 v[188:189], v[188:189], v[228:229]
	v_pk_add_f32 v[190:191], v[190:191], v[228:229]
	v_log_f32_e32 v184, v184
	v_log_f32_e32 v185, v185
	v_log_f32_e32 v186, v186
	v_log_f32_e32 v187, v187
	v_log_f32_e32 v188, v188
	v_log_f32_e32 v189, v189
	v_log_f32_e32 v190, v190
	v_log_f32_e32 v191, v191
	v_pk_mul_f32 v[220:221], v[230:231], v[184:185]
	v_pk_mul_f32 v[222:223], v[230:231], v[186:187]
	v_pk_mul_f32 v[224:225], v[230:231], v[188:189]
	v_pk_mul_f32 v[226:227], v[230:231], v[190:191]
	v_pk_fma_f32 v[220:221], v[184:185], v[230:231], v[220:221] neg_lo:[0,0,1] neg_hi:[0,0,1]
	v_pk_fma_f32 v[222:223], v[186:187], v[230:231], v[222:223] neg_lo:[0,0,1] neg_hi:[0,0,1]
	v_pk_fma_f32 v[224:225], v[188:189], v[230:231], v[224:225] neg_lo:[0,0,1] neg_hi:[0,0,1]
	v_pk_fma_f32 v[226:227], v[190:191], v[230:231], v[226:227] neg_lo:[0,0,1] neg_hi:[0,0,1]
	v_pk_fma_f32 v[220:221], v[232:233], v[184:185], v[220:221]
	v_pk_fma_f32 v[222:223], v[232:233], v[186:187], v[222:223]
	v_pk_fma_f32 v[224:225], v[232:233], v[188:189], v[224:225]
	v_pk_fma_f32 v[226:227], v[232:233], v[190:191], v[226:227]
	v_pk_fma_f32 v[220:221], v[230:231], v[184:185], v[220:221]
	v_pk_fma_f32 v[222:223], v[230:231], v[186:187], v[222:223]
	v_pk_fma_f32 v[224:225], v[230:231], v[188:189], v[224:225]
	v_pk_fma_f32 v[226:227], v[230:231], v[190:191], v[226:227]
	v_pk_add_f32 v[96:97], v[96:97], v[220:221] neg_lo:[0,1] neg_hi:[0,1]
	v_pk_add_f32 v[98:99], v[98:99], v[222:223] neg_lo:[0,1] neg_hi:[0,1]
	v_pk_add_f32 v[92:93], v[92:93], v[224:225] neg_lo:[0,1] neg_hi:[0,1]
	v_pk_add_f32 v[94:95], v[94:95], v[226:227] neg_lo:[0,1] neg_hi:[0,1]
	v_pk_mul_f32 v[96:97], v[234:235], v[96:97]
	v_pk_mul_f32 v[98:99], v[234:235], v[98:99]
	v_pk_mul_f32 v[92:93], v[234:235], v[92:93]
	v_pk_mul_f32 v[94:95], v[234:235], v[94:95]
	v_cvt_pk_bf16_f32 v102, v96, v97
	v_cvt_pk_bf16_f32 v103, v98, v99
	v_cvt_pk_bf16_f32 v104, v92, v93
	v_cvt_pk_bf16_f32 v105, v94, v95
	v_lshl_add_u64 v[100:101], s[16:17], 0, v[108:109]
	v_lshl_add_u64 v[100:101], v[150:151], 1, v[100:101]
	global_store_dwordx4 v[100:101], v[102:105], off
	s_mov_b64 s[10:11], 0

.LBB0_220:
	v_mov_b32_e32 v111, v110
	s_nop 0
	v_mov_b32_e32 v92, v110
	v_mov_b32_e32 v93, v110
	v_pk_mul_f32 v[90:91], v[90:91], v[92:93]
	v_pk_mul_f32 v[88:89], v[88:89], v[110:111]
	v_pk_mul_f32 v[86:87], v[86:87], v[92:93]
	v_pk_mul_f32 v[84:85], v[84:85], v[110:111]
	s_mov_b64 s[36:37], -1
	s_mov_b64 s[34:35], 0
	s_cmp_lt_i32 s54, 9
	s_mov_b64 s[10:11], 0
	s_cbranch_scc1 .LBB0_224
	s_cmp_eq_u32 s54, 9
	s_mov_b64 s[10:11], -1
	s_cbranch_scc0 .LBB0_223
	v_pk_add_f32 v[88:89], v[88:89], v[200:201]
	v_pk_add_f32 v[90:91], v[90:91], v[202:203]
	v_pk_add_f32 v[84:85], v[84:85], v[204:205]
	v_pk_add_f32 v[86:87], v[86:87], v[206:207]
	v_mul_f32_e64 v184, |v88|, s23
	v_mul_f32_e64 v185, |v89|, s23
	v_mul_f32_e64 v186, |v90|, s23
	v_mul_f32_e64 v187, |v91|, s23
	v_mul_f32_e64 v188, |v84|, s23
	v_mul_f32_e64 v189, |v85|, s23
	v_mul_f32_e64 v190, |v86|, s23
	v_mul_f32_e64 v191, |v87|, s23
	v_min_f32_e32 v88, 0, v88
	v_min_f32_e32 v89, 0, v89
	v_min_f32_e32 v90, 0, v90
	v_min_f32_e32 v91, 0, v91
	v_min_f32_e32 v84, 0, v84
	v_min_f32_e32 v85, 0, v85
	v_min_f32_e32 v86, 0, v86
	v_min_f32_e32 v87, 0, v87
	v_exp_f32_e32 v184, v184
	v_exp_f32_e32 v185, v185
	v_exp_f32_e32 v186, v186
	v_exp_f32_e32 v187, v187
	v_exp_f32_e32 v188, v188
	v_exp_f32_e32 v189, v189
	v_exp_f32_e32 v190, v190
	v_exp_f32_e32 v191, v191
	v_pk_add_f32 v[184:185], v[184:185], v[228:229]
	v_pk_add_f32 v[186:187], v[186:187], v[228:229]
	v_pk_add_f32 v[188:189], v[188:189], v[228:229]
	v_pk_add_f32 v[190:191], v[190:191], v[228:229]
	v_log_f32_e32 v184, v184
	v_log_f32_e32 v185, v185
	v_log_f32_e32 v186, v186
	v_log_f32_e32 v187, v187
	v_log_f32_e32 v188, v188
	v_log_f32_e32 v189, v189
	v_log_f32_e32 v190, v190
	v_log_f32_e32 v191, v191
	v_pk_mul_f32 v[220:221], v[230:231], v[184:185]
	v_pk_mul_f32 v[222:223], v[230:231], v[186:187]
	v_pk_mul_f32 v[224:225], v[230:231], v[188:189]
	v_pk_mul_f32 v[226:227], v[230:231], v[190:191]
	v_pk_fma_f32 v[220:221], v[184:185], v[230:231], v[220:221] neg_lo:[0,0,1] neg_hi:[0,0,1]
	v_pk_fma_f32 v[222:223], v[186:187], v[230:231], v[222:223] neg_lo:[0,0,1] neg_hi:[0,0,1]
	v_pk_fma_f32 v[224:225], v[188:189], v[230:231], v[224:225] neg_lo:[0,0,1] neg_hi:[0,0,1]
	v_pk_fma_f32 v[226:227], v[190:191], v[230:231], v[226:227] neg_lo:[0,0,1] neg_hi:[0,0,1]
	v_pk_fma_f32 v[220:221], v[232:233], v[184:185], v[220:221]
	v_pk_fma_f32 v[222:223], v[232:233], v[186:187], v[222:223]
	v_pk_fma_f32 v[224:225], v[232:233], v[188:189], v[224:225]
	v_pk_fma_f32 v[226:227], v[232:233], v[190:191], v[226:227]
	v_pk_fma_f32 v[220:221], v[230:231], v[184:185], v[220:221]
	v_pk_fma_f32 v[222:223], v[230:231], v[186:187], v[222:223]
	v_pk_fma_f32 v[224:225], v[230:231], v[188:189], v[224:225]
	v_pk_fma_f32 v[226:227], v[230:231], v[190:191], v[226:227]
	v_pk_add_f32 v[88:89], v[88:89], v[220:221] neg_lo:[0,1] neg_hi:[0,1]
	v_pk_add_f32 v[90:91], v[90:91], v[222:223] neg_lo:[0,1] neg_hi:[0,1]
	v_pk_add_f32 v[84:85], v[84:85], v[224:225] neg_lo:[0,1] neg_hi:[0,1]
	v_pk_add_f32 v[86:87], v[86:87], v[226:227] neg_lo:[0,1] neg_hi:[0,1]
	v_pk_mul_f32 v[88:89], v[234:235], v[88:89]
	v_pk_mul_f32 v[90:91], v[234:235], v[90:91]
	v_pk_mul_f32 v[84:85], v[234:235], v[84:85]
	v_pk_mul_f32 v[86:87], v[234:235], v[86:87]
	v_cvt_pk_bf16_f32 v94, v88, v89
	v_cvt_pk_bf16_f32 v95, v90, v91
	v_cvt_pk_bf16_f32 v96, v84, v85
	v_cvt_pk_bf16_f32 v97, v86, v87
	v_lshl_add_u64 v[92:93], s[16:17], 0, v[108:109]
	v_lshl_add_u64 v[92:93], v[150:151], 1, v[92:93]
	global_store_dwordx4 v[92:93], v[94:97], off offset:256
	s_mov_b64 s[10:11], 0

.LBB0_232:
	ds_read_b32 v94, v176 offset:192
	v_add_u32_e32 v96, 48, v152
	v_ashrrev_i32_e32 v97, 31, v96
	v_lshlrev_b64 v[92:93], 9, v[96:97]
	s_mov_b64 s[36:37], -1
	s_waitcnt lgkmcnt(0)
	v_pk_mul_f32 v[82:83], v[82:83], v[94:95] op_sel_hi:[1,0]
	v_pk_mul_f32 v[80:81], v[80:81], v[94:95] op_sel_hi:[1,0]
	v_pk_mul_f32 v[78:79], v[78:79], v[94:95] op_sel_hi:[1,0]
	v_pk_mul_f32 v[76:77], v[76:77], v[94:95] op_sel_hi:[1,0]
	s_mov_b64 s[34:35], 0
	s_cmp_lt_i32 s54, 9
	s_mov_b64 s[10:11], 0
	s_cbranch_scc1 .LBB0_238
	s_cmp_eq_u32 s54, 9
	s_mov_b64 s[10:11], -1
	s_cbranch_scc0 .LBB0_235
	v_pk_add_f32 v[80:81], v[80:81], v[192:193]
	v_pk_add_f32 v[82:83], v[82:83], v[194:195]
	v_pk_add_f32 v[76:77], v[76:77], v[196:197]
	v_pk_add_f32 v[78:79], v[78:79], v[198:199]
	v_mul_f32_e64 v184, |v80|, s23
	v_mul_f32_e64 v185, |v81|, s23
	v_mul_f32_e64 v186, |v82|, s23
	v_mul_f32_e64 v187, |v83|, s23
	v_mul_f32_e64 v188, |v76|, s23
	v_mul_f32_e64 v189, |v77|, s23
	v_mul_f32_e64 v190, |v78|, s23
	v_mul_f32_e64 v191, |v79|, s23
	v_min_f32_e32 v80, 0, v80
	v_min_f32_e32 v81, 0, v81
	v_min_f32_e32 v82, 0, v82
	v_min_f32_e32 v83, 0, v83
	v_min_f32_e32 v76, 0, v76
	v_min_f32_e32 v77, 0, v77
	v_min_f32_e32 v78, 0, v78
	v_min_f32_e32 v79, 0, v79
	v_exp_f32_e32 v184, v184
	v_exp_f32_e32 v185, v185
	v_exp_f32_e32 v186, v186
	v_exp_f32_e32 v187, v187
	v_exp_f32_e32 v188, v188
	v_exp_f32_e32 v189, v189
	v_exp_f32_e32 v190, v190
	v_exp_f32_e32 v191, v191
	v_pk_add_f32 v[184:185], v[184:185], v[228:229]
	v_pk_add_f32 v[186:187], v[186:187], v[228:229]
	v_pk_add_f32 v[188:189], v[188:189], v[228:229]
	v_pk_add_f32 v[190:191], v[190:191], v[228:229]
	v_log_f32_e32 v184, v184
	v_log_f32_e32 v185, v185
	v_log_f32_e32 v186, v186
	v_log_f32_e32 v187, v187
	v_log_f32_e32 v188, v188
	v_log_f32_e32 v189, v189
	v_log_f32_e32 v190, v190
	v_log_f32_e32 v191, v191
	v_pk_mul_f32 v[220:221], v[230:231], v[184:185]
	v_pk_mul_f32 v[222:223], v[230:231], v[186:187]
	v_pk_mul_f32 v[224:225], v[230:231], v[188:189]
	v_pk_mul_f32 v[226:227], v[230:231], v[190:191]
	v_pk_fma_f32 v[220:221], v[184:185], v[230:231], v[220:221] neg_lo:[0,0,1] neg_hi:[0,0,1]
	v_pk_fma_f32 v[222:223], v[186:187], v[230:231], v[222:223] neg_lo:[0,0,1] neg_hi:[0,0,1]
	v_pk_fma_f32 v[224:225], v[188:189], v[230:231], v[224:225] neg_lo:[0,0,1] neg_hi:[0,0,1]
	v_pk_fma_f32 v[226:227], v[190:191], v[230:231], v[226:227] neg_lo:[0,0,1] neg_hi:[0,0,1]
	v_pk_fma_f32 v[220:221], v[232:233], v[184:185], v[220:221]
	v_pk_fma_f32 v[222:223], v[232:233], v[186:187], v[222:223]
	v_pk_fma_f32 v[224:225], v[232:233], v[188:189], v[224:225]
	v_pk_fma_f32 v[226:227], v[232:233], v[190:191], v[226:227]
	v_pk_fma_f32 v[220:221], v[230:231], v[184:185], v[220:221]
	v_pk_fma_f32 v[222:223], v[230:231], v[186:187], v[222:223]
	v_pk_fma_f32 v[224:225], v[230:231], v[188:189], v[224:225]
	v_pk_fma_f32 v[226:227], v[230:231], v[190:191], v[226:227]
	v_pk_add_f32 v[80:81], v[80:81], v[220:221] neg_lo:[0,1] neg_hi:[0,1]
	v_pk_add_f32 v[82:83], v[82:83], v[222:223] neg_lo:[0,1] neg_hi:[0,1]
	v_pk_add_f32 v[76:77], v[76:77], v[224:225] neg_lo:[0,1] neg_hi:[0,1]
	v_pk_add_f32 v[78:79], v[78:79], v[226:227] neg_lo:[0,1] neg_hi:[0,1]
	v_pk_mul_f32 v[80:81], v[234:235], v[80:81]
	v_pk_mul_f32 v[82:83], v[234:235], v[82:83]
	v_pk_mul_f32 v[76:77], v[234:235], v[76:77]
	v_pk_mul_f32 v[78:79], v[234:235], v[78:79]
	v_cvt_pk_bf16_f32 v86, v80, v81
	v_cvt_pk_bf16_f32 v87, v82, v83
	v_cvt_pk_bf16_f32 v88, v76, v77
	v_cvt_pk_bf16_f32 v89, v78, v79
	v_lshl_add_u64 v[84:85], s[16:17], 0, v[92:93]
	v_lshl_add_u64 v[84:85], v[150:151], 1, v[84:85]
	global_store_dwordx4 v[84:85], v[86:89], off
	s_mov_b64 s[10:11], 0

.LBB0_248:
	v_mov_b32_e32 v95, v94
	s_nop 0
	v_mov_b32_e32 v76, v94
	v_mov_b32_e32 v77, v94
	v_pk_mul_f32 v[74:75], v[74:75], v[76:77]
	v_pk_mul_f32 v[72:73], v[72:73], v[94:95]
	v_pk_mul_f32 v[70:71], v[70:71], v[76:77]
	v_pk_mul_f32 v[68:69], v[68:69], v[94:95]
	s_mov_b64 s[36:37], -1
	s_mov_b64 s[34:35], 0
	s_cmp_lt_i32 s54, 9
	s_mov_b64 s[10:11], 0
	s_cbranch_scc1 .LBB0_252
	s_cmp_eq_u32 s54, 9
	s_mov_b64 s[10:11], -1
	s_cbranch_scc0 .LBB0_251
	v_pk_add_f32 v[72:73], v[72:73], v[200:201]
	v_pk_add_f32 v[74:75], v[74:75], v[202:203]
	v_pk_add_f32 v[68:69], v[68:69], v[204:205]
	v_pk_add_f32 v[70:71], v[70:71], v[206:207]
	v_mul_f32_e64 v184, |v72|, s23
	v_mul_f32_e64 v185, |v73|, s23
	v_mul_f32_e64 v186, |v74|, s23
	v_mul_f32_e64 v187, |v75|, s23
	v_mul_f32_e64 v188, |v68|, s23
	v_mul_f32_e64 v189, |v69|, s23
	v_mul_f32_e64 v190, |v70|, s23
	v_mul_f32_e64 v191, |v71|, s23
	v_min_f32_e32 v72, 0, v72
	v_min_f32_e32 v73, 0, v73
	v_min_f32_e32 v74, 0, v74
	v_min_f32_e32 v75, 0, v75
	v_min_f32_e32 v68, 0, v68
	v_min_f32_e32 v69, 0, v69
	v_min_f32_e32 v70, 0, v70
	v_min_f32_e32 v71, 0, v71
	v_exp_f32_e32 v184, v184
	v_exp_f32_e32 v185, v185
	v_exp_f32_e32 v186, v186
	v_exp_f32_e32 v187, v187
	v_exp_f32_e32 v188, v188
	v_exp_f32_e32 v189, v189
	v_exp_f32_e32 v190, v190
	v_exp_f32_e32 v191, v191
	v_pk_add_f32 v[184:185], v[184:185], v[228:229]
	v_pk_add_f32 v[186:187], v[186:187], v[228:229]
	v_pk_add_f32 v[188:189], v[188:189], v[228:229]
	v_pk_add_f32 v[190:191], v[190:191], v[228:229]
	v_log_f32_e32 v184, v184
	v_log_f32_e32 v185, v185
	v_log_f32_e32 v186, v186
	v_log_f32_e32 v187, v187
	v_log_f32_e32 v188, v188
	v_log_f32_e32 v189, v189
	v_log_f32_e32 v190, v190
	v_log_f32_e32 v191, v191
	v_pk_mul_f32 v[220:221], v[230:231], v[184:185]
	v_pk_mul_f32 v[222:223], v[230:231], v[186:187]
	v_pk_mul_f32 v[224:225], v[230:231], v[188:189]
	v_pk_mul_f32 v[226:227], v[230:231], v[190:191]
	v_pk_fma_f32 v[220:221], v[184:185], v[230:231], v[220:221] neg_lo:[0,0,1] neg_hi:[0,0,1]
	v_pk_fma_f32 v[222:223], v[186:187], v[230:231], v[222:223] neg_lo:[0,0,1] neg_hi:[0,0,1]
	v_pk_fma_f32 v[224:225], v[188:189], v[230:231], v[224:225] neg_lo:[0,0,1] neg_hi:[0,0,1]
	v_pk_fma_f32 v[226:227], v[190:191], v[230:231], v[226:227] neg_lo:[0,0,1] neg_hi:[0,0,1]
	v_pk_fma_f32 v[220:221], v[232:233], v[184:185], v[220:221]
	v_pk_fma_f32 v[222:223], v[232:233], v[186:187], v[222:223]
	v_pk_fma_f32 v[224:225], v[232:233], v[188:189], v[224:225]
	v_pk_fma_f32 v[226:227], v[232:233], v[190:191], v[226:227]
	v_pk_fma_f32 v[220:221], v[230:231], v[184:185], v[220:221]
	v_pk_fma_f32 v[222:223], v[230:231], v[186:187], v[222:223]
	v_pk_fma_f32 v[224:225], v[230:231], v[188:189], v[224:225]
	v_pk_fma_f32 v[226:227], v[230:231], v[190:191], v[226:227]
	v_pk_add_f32 v[72:73], v[72:73], v[220:221] neg_lo:[0,1] neg_hi:[0,1]
	v_pk_add_f32 v[74:75], v[74:75], v[222:223] neg_lo:[0,1] neg_hi:[0,1]
	v_pk_add_f32 v[68:69], v[68:69], v[224:225] neg_lo:[0,1] neg_hi:[0,1]
	v_pk_add_f32 v[70:71], v[70:71], v[226:227] neg_lo:[0,1] neg_hi:[0,1]
	v_pk_mul_f32 v[72:73], v[234:235], v[72:73]
	v_pk_mul_f32 v[74:75], v[234:235], v[74:75]
	v_pk_mul_f32 v[68:69], v[234:235], v[68:69]
	v_pk_mul_f32 v[70:71], v[234:235], v[70:71]
	v_cvt_pk_bf16_f32 v78, v72, v73
	v_cvt_pk_bf16_f32 v79, v74, v75
	v_cvt_pk_bf16_f32 v80, v68, v69
	v_cvt_pk_bf16_f32 v81, v70, v71
	v_lshl_add_u64 v[76:77], s[16:17], 0, v[92:93]
	v_lshl_add_u64 v[76:77], v[150:151], 1, v[76:77]
	global_store_dwordx4 v[76:77], v[78:81], off offset:256
	s_mov_b64 s[10:11], 0

.LBB0_260:
	ds_read_b32 v78, v176 offset:512
	v_add_u32_e32 v80, 0x80, v152
	v_ashrrev_i32_e32 v81, 31, v80
	v_lshlrev_b64 v[76:77], 9, v[80:81]
	s_mov_b64 s[36:37], -1
	s_waitcnt lgkmcnt(0)
	v_pk_mul_f32 v[66:67], v[66:67], v[78:79] op_sel_hi:[1,0]
	v_pk_mul_f32 v[64:65], v[64:65], v[78:79] op_sel_hi:[1,0]
	v_pk_mul_f32 v[62:63], v[62:63], v[78:79] op_sel_hi:[1,0]
	v_pk_mul_f32 v[60:61], v[60:61], v[78:79] op_sel_hi:[1,0]
	s_mov_b64 s[34:35], 0
	s_cmp_lt_i32 s54, 9
	s_mov_b64 s[10:11], 0
	s_cbranch_scc1 .LBB0_266
	s_cmp_eq_u32 s54, 9
	s_mov_b64 s[10:11], -1
	s_cbranch_scc0 .LBB0_263
	v_pk_add_f32 v[64:65], v[64:65], v[192:193]
	v_pk_add_f32 v[66:67], v[66:67], v[194:195]
	v_pk_add_f32 v[60:61], v[60:61], v[196:197]
	v_pk_add_f32 v[62:63], v[62:63], v[198:199]
	v_mul_f32_e64 v184, |v64|, s23
	v_mul_f32_e64 v185, |v65|, s23
	v_mul_f32_e64 v186, |v66|, s23
	v_mul_f32_e64 v187, |v67|, s23
	v_mul_f32_e64 v188, |v60|, s23
	v_mul_f32_e64 v189, |v61|, s23
	v_mul_f32_e64 v190, |v62|, s23
	v_mul_f32_e64 v191, |v63|, s23
	v_min_f32_e32 v64, 0, v64
	v_min_f32_e32 v65, 0, v65
	v_min_f32_e32 v66, 0, v66
	v_min_f32_e32 v67, 0, v67
	v_min_f32_e32 v60, 0, v60
	v_min_f32_e32 v61, 0, v61
	v_min_f32_e32 v62, 0, v62
	v_min_f32_e32 v63, 0, v63
	v_exp_f32_e32 v184, v184
	v_exp_f32_e32 v185, v185
	v_exp_f32_e32 v186, v186
	v_exp_f32_e32 v187, v187
	v_exp_f32_e32 v188, v188
	v_exp_f32_e32 v189, v189
	v_exp_f32_e32 v190, v190
	v_exp_f32_e32 v191, v191
	v_pk_add_f32 v[184:185], v[184:185], v[228:229]
	v_pk_add_f32 v[186:187], v[186:187], v[228:229]
	v_pk_add_f32 v[188:189], v[188:189], v[228:229]
	v_pk_add_f32 v[190:191], v[190:191], v[228:229]
	v_log_f32_e32 v184, v184
	v_log_f32_e32 v185, v185
	v_log_f32_e32 v186, v186
	v_log_f32_e32 v187, v187
	v_log_f32_e32 v188, v188
	v_log_f32_e32 v189, v189
	v_log_f32_e32 v190, v190
	v_log_f32_e32 v191, v191
	v_pk_mul_f32 v[220:221], v[230:231], v[184:185]
	v_pk_mul_f32 v[222:223], v[230:231], v[186:187]
	v_pk_mul_f32 v[224:225], v[230:231], v[188:189]
	v_pk_mul_f32 v[226:227], v[230:231], v[190:191]
	v_pk_fma_f32 v[220:221], v[184:185], v[230:231], v[220:221] neg_lo:[0,0,1] neg_hi:[0,0,1]
	v_pk_fma_f32 v[222:223], v[186:187], v[230:231], v[222:223] neg_lo:[0,0,1] neg_hi:[0,0,1]
	v_pk_fma_f32 v[224:225], v[188:189], v[230:231], v[224:225] neg_lo:[0,0,1] neg_hi:[0,0,1]
	v_pk_fma_f32 v[226:227], v[190:191], v[230:231], v[226:227] neg_lo:[0,0,1] neg_hi:[0,0,1]
	v_pk_fma_f32 v[220:221], v[232:233], v[184:185], v[220:221]
	v_pk_fma_f32 v[222:223], v[232:233], v[186:187], v[222:223]
	v_pk_fma_f32 v[224:225], v[232:233], v[188:189], v[224:225]
	v_pk_fma_f32 v[226:227], v[232:233], v[190:191], v[226:227]
	v_pk_fma_f32 v[220:221], v[230:231], v[184:185], v[220:221]
	v_pk_fma_f32 v[222:223], v[230:231], v[186:187], v[222:223]
	v_pk_fma_f32 v[224:225], v[230:231], v[188:189], v[224:225]
	v_pk_fma_f32 v[226:227], v[230:231], v[190:191], v[226:227]
	v_pk_add_f32 v[64:65], v[64:65], v[220:221] neg_lo:[0,1] neg_hi:[0,1]
	v_pk_add_f32 v[66:67], v[66:67], v[222:223] neg_lo:[0,1] neg_hi:[0,1]
	v_pk_add_f32 v[60:61], v[60:61], v[224:225] neg_lo:[0,1] neg_hi:[0,1]
	v_pk_add_f32 v[62:63], v[62:63], v[226:227] neg_lo:[0,1] neg_hi:[0,1]
	v_pk_mul_f32 v[64:65], v[234:235], v[64:65]
	v_pk_mul_f32 v[66:67], v[234:235], v[66:67]
	v_pk_mul_f32 v[60:61], v[234:235], v[60:61]
	v_pk_mul_f32 v[62:63], v[234:235], v[62:63]
	v_cvt_pk_bf16_f32 v70, v64, v65
	v_cvt_pk_bf16_f32 v71, v66, v67
	v_cvt_pk_bf16_f32 v72, v60, v61
	v_cvt_pk_bf16_f32 v73, v62, v63
	v_lshl_add_u64 v[68:69], s[16:17], 0, v[76:77]
	v_lshl_add_u64 v[68:69], v[150:151], 1, v[68:69]
	global_store_dwordx4 v[68:69], v[70:73], off
	s_mov_b64 s[10:11], 0

.LBB0_276:
	v_mov_b32_e32 v79, v78
	s_nop 0
	v_mov_b32_e32 v60, v78
	v_mov_b32_e32 v61, v78
	v_pk_mul_f32 v[58:59], v[58:59], v[60:61]
	v_pk_mul_f32 v[56:57], v[56:57], v[78:79]
	v_pk_mul_f32 v[54:55], v[54:55], v[60:61]
	v_pk_mul_f32 v[52:53], v[52:53], v[78:79]
	s_mov_b64 s[36:37], -1
	s_mov_b64 s[34:35], 0
	s_cmp_lt_i32 s54, 9
	s_mov_b64 s[10:11], 0
	s_cbranch_scc1 .LBB0_280
	s_cmp_eq_u32 s54, 9
	s_mov_b64 s[10:11], -1
	s_cbranch_scc0 .LBB0_279
	v_pk_add_f32 v[56:57], v[56:57], v[200:201]
	v_pk_add_f32 v[58:59], v[58:59], v[202:203]
	v_pk_add_f32 v[52:53], v[52:53], v[204:205]
	v_pk_add_f32 v[54:55], v[54:55], v[206:207]
	v_mul_f32_e64 v184, |v56|, s23
	v_mul_f32_e64 v185, |v57|, s23
	v_mul_f32_e64 v186, |v58|, s23
	v_mul_f32_e64 v187, |v59|, s23
	v_mul_f32_e64 v188, |v52|, s23
	v_mul_f32_e64 v189, |v53|, s23
	v_mul_f32_e64 v190, |v54|, s23
	v_mul_f32_e64 v191, |v55|, s23
	v_min_f32_e32 v56, 0, v56
	v_min_f32_e32 v57, 0, v57
	v_min_f32_e32 v58, 0, v58
	v_min_f32_e32 v59, 0, v59
	v_min_f32_e32 v52, 0, v52
	v_min_f32_e32 v53, 0, v53
	v_min_f32_e32 v54, 0, v54
	v_min_f32_e32 v55, 0, v55
	v_exp_f32_e32 v184, v184
	v_exp_f32_e32 v185, v185
	v_exp_f32_e32 v186, v186
	v_exp_f32_e32 v187, v187
	v_exp_f32_e32 v188, v188
	v_exp_f32_e32 v189, v189
	v_exp_f32_e32 v190, v190
	v_exp_f32_e32 v191, v191
	v_pk_add_f32 v[184:185], v[184:185], v[228:229]
	v_pk_add_f32 v[186:187], v[186:187], v[228:229]
	v_pk_add_f32 v[188:189], v[188:189], v[228:229]
	v_pk_add_f32 v[190:191], v[190:191], v[228:229]
	v_log_f32_e32 v184, v184
	v_log_f32_e32 v185, v185
	v_log_f32_e32 v186, v186
	v_log_f32_e32 v187, v187
	v_log_f32_e32 v188, v188
	v_log_f32_e32 v189, v189
	v_log_f32_e32 v190, v190
	v_log_f32_e32 v191, v191
	v_pk_mul_f32 v[220:221], v[230:231], v[184:185]
	v_pk_mul_f32 v[222:223], v[230:231], v[186:187]
	v_pk_mul_f32 v[224:225], v[230:231], v[188:189]
	v_pk_mul_f32 v[226:227], v[230:231], v[190:191]
	v_pk_fma_f32 v[220:221], v[184:185], v[230:231], v[220:221] neg_lo:[0,0,1] neg_hi:[0,0,1]
	v_pk_fma_f32 v[222:223], v[186:187], v[230:231], v[222:223] neg_lo:[0,0,1] neg_hi:[0,0,1]
	v_pk_fma_f32 v[224:225], v[188:189], v[230:231], v[224:225] neg_lo:[0,0,1] neg_hi:[0,0,1]
	v_pk_fma_f32 v[226:227], v[190:191], v[230:231], v[226:227] neg_lo:[0,0,1] neg_hi:[0,0,1]
	v_pk_fma_f32 v[220:221], v[232:233], v[184:185], v[220:221]
	v_pk_fma_f32 v[222:223], v[232:233], v[186:187], v[222:223]
	v_pk_fma_f32 v[224:225], v[232:233], v[188:189], v[224:225]
	v_pk_fma_f32 v[226:227], v[232:233], v[190:191], v[226:227]
	v_pk_fma_f32 v[220:221], v[230:231], v[184:185], v[220:221]
	v_pk_fma_f32 v[222:223], v[230:231], v[186:187], v[222:223]
	v_pk_fma_f32 v[224:225], v[230:231], v[188:189], v[224:225]
	v_pk_fma_f32 v[226:227], v[230:231], v[190:191], v[226:227]
	v_pk_add_f32 v[56:57], v[56:57], v[220:221] neg_lo:[0,1] neg_hi:[0,1]
	v_pk_add_f32 v[58:59], v[58:59], v[222:223] neg_lo:[0,1] neg_hi:[0,1]
	v_pk_add_f32 v[52:53], v[52:53], v[224:225] neg_lo:[0,1] neg_hi:[0,1]
	v_pk_add_f32 v[54:55], v[54:55], v[226:227] neg_lo:[0,1] neg_hi:[0,1]
	v_pk_mul_f32 v[56:57], v[234:235], v[56:57]
	v_pk_mul_f32 v[58:59], v[234:235], v[58:59]
	v_pk_mul_f32 v[52:53], v[234:235], v[52:53]
	v_pk_mul_f32 v[54:55], v[234:235], v[54:55]
	v_cvt_pk_bf16_f32 v62, v56, v57
	v_cvt_pk_bf16_f32 v63, v58, v59
	v_cvt_pk_bf16_f32 v64, v52, v53
	v_cvt_pk_bf16_f32 v65, v54, v55
	v_lshl_add_u64 v[60:61], s[16:17], 0, v[76:77]
	v_lshl_add_u64 v[60:61], v[150:151], 1, v[60:61]
	global_store_dwordx4 v[60:61], v[62:65], off offset:256
	s_mov_b64 s[10:11], 0

.LBB0_288:
	ds_read_b32 v62, v176 offset:576
	v_add_u32_e32 v64, 0x90, v152
	v_ashrrev_i32_e32 v65, 31, v64
	v_lshlrev_b64 v[60:61], 9, v[64:65]
	s_mov_b64 s[36:37], -1
	s_waitcnt lgkmcnt(0)
	v_pk_mul_f32 v[50:51], v[50:51], v[62:63] op_sel_hi:[1,0]
	v_pk_mul_f32 v[48:49], v[48:49], v[62:63] op_sel_hi:[1,0]
	v_pk_mul_f32 v[46:47], v[46:47], v[62:63] op_sel_hi:[1,0]
	v_pk_mul_f32 v[44:45], v[44:45], v[62:63] op_sel_hi:[1,0]
	s_mov_b64 s[34:35], 0
	s_cmp_lt_i32 s54, 9
	s_mov_b64 s[10:11], 0
	s_cbranch_scc1 .LBB0_294
	s_cmp_eq_u32 s54, 9
	s_mov_b64 s[10:11], -1
	s_cbranch_scc0 .LBB0_291
	v_pk_add_f32 v[48:49], v[48:49], v[192:193]
	v_pk_add_f32 v[50:51], v[50:51], v[194:195]
	v_pk_add_f32 v[44:45], v[44:45], v[196:197]
	v_pk_add_f32 v[46:47], v[46:47], v[198:199]
	v_mul_f32_e64 v184, |v48|, s23
	v_mul_f32_e64 v185, |v49|, s23
	v_mul_f32_e64 v186, |v50|, s23
	v_mul_f32_e64 v187, |v51|, s23
	v_mul_f32_e64 v188, |v44|, s23
	v_mul_f32_e64 v189, |v45|, s23
	v_mul_f32_e64 v190, |v46|, s23
	v_mul_f32_e64 v191, |v47|, s23
	v_min_f32_e32 v48, 0, v48
	v_min_f32_e32 v49, 0, v49
	v_min_f32_e32 v50, 0, v50
	v_min_f32_e32 v51, 0, v51
	v_min_f32_e32 v44, 0, v44
	v_min_f32_e32 v45, 0, v45
	v_min_f32_e32 v46, 0, v46
	v_min_f32_e32 v47, 0, v47
	v_exp_f32_e32 v184, v184
	v_exp_f32_e32 v185, v185
	v_exp_f32_e32 v186, v186
	v_exp_f32_e32 v187, v187
	v_exp_f32_e32 v188, v188
	v_exp_f32_e32 v189, v189
	v_exp_f32_e32 v190, v190
	v_exp_f32_e32 v191, v191
	v_pk_add_f32 v[184:185], v[184:185], v[228:229]
	v_pk_add_f32 v[186:187], v[186:187], v[228:229]
	v_pk_add_f32 v[188:189], v[188:189], v[228:229]
	v_pk_add_f32 v[190:191], v[190:191], v[228:229]
	v_log_f32_e32 v184, v184
	v_log_f32_e32 v185, v185
	v_log_f32_e32 v186, v186
	v_log_f32_e32 v187, v187
	v_log_f32_e32 v188, v188
	v_log_f32_e32 v189, v189
	v_log_f32_e32 v190, v190
	v_log_f32_e32 v191, v191
	v_pk_mul_f32 v[220:221], v[230:231], v[184:185]
	v_pk_mul_f32 v[222:223], v[230:231], v[186:187]
	v_pk_mul_f32 v[224:225], v[230:231], v[188:189]
	v_pk_mul_f32 v[226:227], v[230:231], v[190:191]
	v_pk_fma_f32 v[220:221], v[184:185], v[230:231], v[220:221] neg_lo:[0,0,1] neg_hi:[0,0,1]
	v_pk_fma_f32 v[222:223], v[186:187], v[230:231], v[222:223] neg_lo:[0,0,1] neg_hi:[0,0,1]
	v_pk_fma_f32 v[224:225], v[188:189], v[230:231], v[224:225] neg_lo:[0,0,1] neg_hi:[0,0,1]
	v_pk_fma_f32 v[226:227], v[190:191], v[230:231], v[226:227] neg_lo:[0,0,1] neg_hi:[0,0,1]
	v_pk_fma_f32 v[220:221], v[232:233], v[184:185], v[220:221]
	v_pk_fma_f32 v[222:223], v[232:233], v[186:187], v[222:223]
	v_pk_fma_f32 v[224:225], v[232:233], v[188:189], v[224:225]
	v_pk_fma_f32 v[226:227], v[232:233], v[190:191], v[226:227]
	v_pk_fma_f32 v[220:221], v[230:231], v[184:185], v[220:221]
	v_pk_fma_f32 v[222:223], v[230:231], v[186:187], v[222:223]
	v_pk_fma_f32 v[224:225], v[230:231], v[188:189], v[224:225]
	v_pk_fma_f32 v[226:227], v[230:231], v[190:191], v[226:227]
	v_pk_add_f32 v[48:49], v[48:49], v[220:221] neg_lo:[0,1] neg_hi:[0,1]
	v_pk_add_f32 v[50:51], v[50:51], v[222:223] neg_lo:[0,1] neg_hi:[0,1]
	v_pk_add_f32 v[44:45], v[44:45], v[224:225] neg_lo:[0,1] neg_hi:[0,1]
	v_pk_add_f32 v[46:47], v[46:47], v[226:227] neg_lo:[0,1] neg_hi:[0,1]
	v_pk_mul_f32 v[48:49], v[234:235], v[48:49]
	v_pk_mul_f32 v[50:51], v[234:235], v[50:51]
	v_pk_mul_f32 v[44:45], v[234:235], v[44:45]
	v_pk_mul_f32 v[46:47], v[234:235], v[46:47]
	v_cvt_pk_bf16_f32 v54, v48, v49
	v_cvt_pk_bf16_f32 v55, v50, v51
	v_cvt_pk_bf16_f32 v56, v44, v45
	v_cvt_pk_bf16_f32 v57, v46, v47
	v_lshl_add_u64 v[52:53], s[16:17], 0, v[60:61]
	v_lshl_add_u64 v[52:53], v[150:151], 1, v[52:53]
	global_store_dwordx4 v[52:53], v[54:57], off
	s_mov_b64 s[10:11], 0

.LBB0_304:
	v_mov_b32_e32 v63, v62
	s_nop 0
	v_mov_b32_e32 v44, v62
	v_mov_b32_e32 v45, v62
	v_pk_mul_f32 v[42:43], v[42:43], v[44:45]
	v_pk_mul_f32 v[40:41], v[40:41], v[62:63]
	v_pk_mul_f32 v[38:39], v[38:39], v[44:45]
	v_pk_mul_f32 v[36:37], v[36:37], v[62:63]
	s_mov_b64 s[36:37], -1
	s_mov_b64 s[34:35], 0
	s_cmp_lt_i32 s54, 9
	s_mov_b64 s[10:11], 0
	s_cbranch_scc1 .LBB0_308
	s_cmp_eq_u32 s54, 9
	s_mov_b64 s[10:11], -1
	s_cbranch_scc0 .LBB0_307
	v_pk_add_f32 v[40:41], v[40:41], v[200:201]
	v_pk_add_f32 v[42:43], v[42:43], v[202:203]
	v_pk_add_f32 v[36:37], v[36:37], v[204:205]
	v_pk_add_f32 v[38:39], v[38:39], v[206:207]
	v_mul_f32_e64 v184, |v40|, s23
	v_mul_f32_e64 v185, |v41|, s23
	v_mul_f32_e64 v186, |v42|, s23
	v_mul_f32_e64 v187, |v43|, s23
	v_mul_f32_e64 v188, |v36|, s23
	v_mul_f32_e64 v189, |v37|, s23
	v_mul_f32_e64 v190, |v38|, s23
	v_mul_f32_e64 v191, |v39|, s23
	v_min_f32_e32 v40, 0, v40
	v_min_f32_e32 v41, 0, v41
	v_min_f32_e32 v42, 0, v42
	v_min_f32_e32 v43, 0, v43
	v_min_f32_e32 v36, 0, v36
	v_min_f32_e32 v37, 0, v37
	v_min_f32_e32 v38, 0, v38
	v_min_f32_e32 v39, 0, v39
	v_exp_f32_e32 v184, v184
	v_exp_f32_e32 v185, v185
	v_exp_f32_e32 v186, v186
	v_exp_f32_e32 v187, v187
	v_exp_f32_e32 v188, v188
	v_exp_f32_e32 v189, v189
	v_exp_f32_e32 v190, v190
	v_exp_f32_e32 v191, v191
	v_pk_add_f32 v[184:185], v[184:185], v[228:229]
	v_pk_add_f32 v[186:187], v[186:187], v[228:229]
	v_pk_add_f32 v[188:189], v[188:189], v[228:229]
	v_pk_add_f32 v[190:191], v[190:191], v[228:229]
	v_log_f32_e32 v184, v184
	v_log_f32_e32 v185, v185
	v_log_f32_e32 v186, v186
	v_log_f32_e32 v187, v187
	v_log_f32_e32 v188, v188
	v_log_f32_e32 v189, v189
	v_log_f32_e32 v190, v190
	v_log_f32_e32 v191, v191
	v_pk_mul_f32 v[220:221], v[230:231], v[184:185]
	v_pk_mul_f32 v[222:223], v[230:231], v[186:187]
	v_pk_mul_f32 v[224:225], v[230:231], v[188:189]
	v_pk_mul_f32 v[226:227], v[230:231], v[190:191]
	v_pk_fma_f32 v[220:221], v[184:185], v[230:231], v[220:221] neg_lo:[0,0,1] neg_hi:[0,0,1]
	v_pk_fma_f32 v[222:223], v[186:187], v[230:231], v[222:223] neg_lo:[0,0,1] neg_hi:[0,0,1]
	v_pk_fma_f32 v[224:225], v[188:189], v[230:231], v[224:225] neg_lo:[0,0,1] neg_hi:[0,0,1]
	v_pk_fma_f32 v[226:227], v[190:191], v[230:231], v[226:227] neg_lo:[0,0,1] neg_hi:[0,0,1]
	v_pk_fma_f32 v[220:221], v[232:233], v[184:185], v[220:221]
	v_pk_fma_f32 v[222:223], v[232:233], v[186:187], v[222:223]
	v_pk_fma_f32 v[224:225], v[232:233], v[188:189], v[224:225]
	v_pk_fma_f32 v[226:227], v[232:233], v[190:191], v[226:227]
	v_pk_fma_f32 v[220:221], v[230:231], v[184:185], v[220:221]
	v_pk_fma_f32 v[222:223], v[230:231], v[186:187], v[222:223]
	v_pk_fma_f32 v[224:225], v[230:231], v[188:189], v[224:225]
	v_pk_fma_f32 v[226:227], v[230:231], v[190:191], v[226:227]
	v_pk_add_f32 v[40:41], v[40:41], v[220:221] neg_lo:[0,1] neg_hi:[0,1]
	v_pk_add_f32 v[42:43], v[42:43], v[222:223] neg_lo:[0,1] neg_hi:[0,1]
	v_pk_add_f32 v[36:37], v[36:37], v[224:225] neg_lo:[0,1] neg_hi:[0,1]
	v_pk_add_f32 v[38:39], v[38:39], v[226:227] neg_lo:[0,1] neg_hi:[0,1]
	v_pk_mul_f32 v[40:41], v[234:235], v[40:41]
	v_pk_mul_f32 v[42:43], v[234:235], v[42:43]
	v_pk_mul_f32 v[36:37], v[234:235], v[36:37]
	v_pk_mul_f32 v[38:39], v[234:235], v[38:39]
	v_cvt_pk_bf16_f32 v46, v40, v41
	v_cvt_pk_bf16_f32 v47, v42, v43
	v_cvt_pk_bf16_f32 v48, v36, v37
	v_cvt_pk_bf16_f32 v49, v38, v39
	v_lshl_add_u64 v[44:45], s[16:17], 0, v[60:61]
	v_lshl_add_u64 v[44:45], v[150:151], 1, v[44:45]
	global_store_dwordx4 v[44:45], v[46:49], off offset:256
	s_mov_b64 s[10:11], 0

.LBB0_316:
	ds_read_b32 v46, v176 offset:640
	v_add_u32_e32 v48, 0xa0, v152
	v_ashrrev_i32_e32 v49, 31, v48
	v_lshlrev_b64 v[44:45], 9, v[48:49]
	s_mov_b64 s[36:37], -1
	s_waitcnt lgkmcnt(0)
	v_pk_mul_f32 v[34:35], v[34:35], v[46:47] op_sel_hi:[1,0]
	v_pk_mul_f32 v[32:33], v[32:33], v[46:47] op_sel_hi:[1,0]
	v_pk_mul_f32 v[30:31], v[30:31], v[46:47] op_sel_hi:[1,0]
	v_pk_mul_f32 v[28:29], v[28:29], v[46:47] op_sel_hi:[1,0]
	s_mov_b64 s[34:35], 0
	s_cmp_lt_i32 s54, 9
	s_mov_b64 s[10:11], 0
	s_cbranch_scc1 .LBB0_322
	s_cmp_eq_u32 s54, 9
	s_mov_b64 s[10:11], -1
	s_cbranch_scc0 .LBB0_319
	v_pk_add_f32 v[32:33], v[32:33], v[192:193]
	v_pk_add_f32 v[34:35], v[34:35], v[194:195]
	v_pk_add_f32 v[28:29], v[28:29], v[196:197]
	v_pk_add_f32 v[30:31], v[30:31], v[198:199]
	v_mul_f32_e64 v184, |v32|, s23
	v_mul_f32_e64 v185, |v33|, s23
	v_mul_f32_e64 v186, |v34|, s23
	v_mul_f32_e64 v187, |v35|, s23
	v_mul_f32_e64 v188, |v28|, s23
	v_mul_f32_e64 v189, |v29|, s23
	v_mul_f32_e64 v190, |v30|, s23
	v_mul_f32_e64 v191, |v31|, s23
	v_min_f32_e32 v32, 0, v32
	v_min_f32_e32 v33, 0, v33
	v_min_f32_e32 v34, 0, v34
	v_min_f32_e32 v35, 0, v35
	v_min_f32_e32 v28, 0, v28
	v_min_f32_e32 v29, 0, v29
	v_min_f32_e32 v30, 0, v30
	v_min_f32_e32 v31, 0, v31
	v_exp_f32_e32 v184, v184
	v_exp_f32_e32 v185, v185
	v_exp_f32_e32 v186, v186
	v_exp_f32_e32 v187, v187
	v_exp_f32_e32 v188, v188
	v_exp_f32_e32 v189, v189
	v_exp_f32_e32 v190, v190
	v_exp_f32_e32 v191, v191
	v_pk_add_f32 v[184:185], v[184:185], v[228:229]
	v_pk_add_f32 v[186:187], v[186:187], v[228:229]
	v_pk_add_f32 v[188:189], v[188:189], v[228:229]
	v_pk_add_f32 v[190:191], v[190:191], v[228:229]
	v_log_f32_e32 v184, v184
	v_log_f32_e32 v185, v185
	v_log_f32_e32 v186, v186
	v_log_f32_e32 v187, v187
	v_log_f32_e32 v188, v188
	v_log_f32_e32 v189, v189
	v_log_f32_e32 v190, v190
	v_log_f32_e32 v191, v191
	v_pk_mul_f32 v[220:221], v[230:231], v[184:185]
	v_pk_mul_f32 v[222:223], v[230:231], v[186:187]
	v_pk_mul_f32 v[224:225], v[230:231], v[188:189]
	v_pk_mul_f32 v[226:227], v[230:231], v[190:191]
	v_pk_fma_f32 v[220:221], v[184:185], v[230:231], v[220:221] neg_lo:[0,0,1] neg_hi:[0,0,1]
	v_pk_fma_f32 v[222:223], v[186:187], v[230:231], v[222:223] neg_lo:[0,0,1] neg_hi:[0,0,1]
	v_pk_fma_f32 v[224:225], v[188:189], v[230:231], v[224:225] neg_lo:[0,0,1] neg_hi:[0,0,1]
	v_pk_fma_f32 v[226:227], v[190:191], v[230:231], v[226:227] neg_lo:[0,0,1] neg_hi:[0,0,1]
	v_pk_fma_f32 v[220:221], v[232:233], v[184:185], v[220:221]
	v_pk_fma_f32 v[222:223], v[232:233], v[186:187], v[222:223]
	v_pk_fma_f32 v[224:225], v[232:233], v[188:189], v[224:225]
	v_pk_fma_f32 v[226:227], v[232:233], v[190:191], v[226:227]
	v_pk_fma_f32 v[220:221], v[230:231], v[184:185], v[220:221]
	v_pk_fma_f32 v[222:223], v[230:231], v[186:187], v[222:223]
	v_pk_fma_f32 v[224:225], v[230:231], v[188:189], v[224:225]
	v_pk_fma_f32 v[226:227], v[230:231], v[190:191], v[226:227]
	v_pk_add_f32 v[32:33], v[32:33], v[220:221] neg_lo:[0,1] neg_hi:[0,1]
	v_pk_add_f32 v[34:35], v[34:35], v[222:223] neg_lo:[0,1] neg_hi:[0,1]
	v_pk_add_f32 v[28:29], v[28:29], v[224:225] neg_lo:[0,1] neg_hi:[0,1]
	v_pk_add_f32 v[30:31], v[30:31], v[226:227] neg_lo:[0,1] neg_hi:[0,1]
	v_pk_mul_f32 v[32:33], v[234:235], v[32:33]
	v_pk_mul_f32 v[34:35], v[234:235], v[34:35]
	v_pk_mul_f32 v[28:29], v[234:235], v[28:29]
	v_pk_mul_f32 v[30:31], v[234:235], v[30:31]
	v_cvt_pk_bf16_f32 v38, v32, v33
	v_cvt_pk_bf16_f32 v39, v34, v35
	v_cvt_pk_bf16_f32 v40, v28, v29
	v_cvt_pk_bf16_f32 v41, v30, v31
	v_lshl_add_u64 v[36:37], s[16:17], 0, v[44:45]
	v_lshl_add_u64 v[36:37], v[150:151], 1, v[36:37]
	global_store_dwordx4 v[36:37], v[38:41], off
	s_mov_b64 s[10:11], 0

.LBB0_332:
	v_mov_b32_e32 v47, v46
	s_nop 0
	v_mov_b32_e32 v28, v46
	v_mov_b32_e32 v29, v46
	v_pk_mul_f32 v[26:27], v[26:27], v[28:29]
	v_pk_mul_f32 v[24:25], v[24:25], v[46:47]
	v_pk_mul_f32 v[22:23], v[22:23], v[28:29]
	v_pk_mul_f32 v[20:21], v[20:21], v[46:47]
	s_mov_b64 s[36:37], -1
	s_mov_b64 s[34:35], 0
	s_cmp_lt_i32 s54, 9
	s_mov_b64 s[10:11], 0
	s_cbranch_scc1 .LBB0_336
	s_cmp_eq_u32 s54, 9
	s_mov_b64 s[10:11], -1
	s_cbranch_scc0 .LBB0_335
	v_pk_add_f32 v[24:25], v[24:25], v[200:201]
	v_pk_add_f32 v[26:27], v[26:27], v[202:203]
	v_pk_add_f32 v[20:21], v[20:21], v[204:205]
	v_pk_add_f32 v[22:23], v[22:23], v[206:207]
	v_mul_f32_e64 v184, |v24|, s23
	v_mul_f32_e64 v185, |v25|, s23
	v_mul_f32_e64 v186, |v26|, s23
	v_mul_f32_e64 v187, |v27|, s23
	v_mul_f32_e64 v188, |v20|, s23
	v_mul_f32_e64 v189, |v21|, s23
	v_mul_f32_e64 v190, |v22|, s23
	v_mul_f32_e64 v191, |v23|, s23
	v_min_f32_e32 v24, 0, v24
	v_min_f32_e32 v25, 0, v25
	v_min_f32_e32 v26, 0, v26
	v_min_f32_e32 v27, 0, v27
	v_min_f32_e32 v20, 0, v20
	v_min_f32_e32 v21, 0, v21
	v_min_f32_e32 v22, 0, v22
	v_min_f32_e32 v23, 0, v23
	v_exp_f32_e32 v184, v184
	v_exp_f32_e32 v185, v185
	v_exp_f32_e32 v186, v186
	v_exp_f32_e32 v187, v187
	v_exp_f32_e32 v188, v188
	v_exp_f32_e32 v189, v189
	v_exp_f32_e32 v190, v190
	v_exp_f32_e32 v191, v191
	v_pk_add_f32 v[184:185], v[184:185], v[228:229]
	v_pk_add_f32 v[186:187], v[186:187], v[228:229]
	v_pk_add_f32 v[188:189], v[188:189], v[228:229]
	v_pk_add_f32 v[190:191], v[190:191], v[228:229]
	v_log_f32_e32 v184, v184
	v_log_f32_e32 v185, v185
	v_log_f32_e32 v186, v186
	v_log_f32_e32 v187, v187
	v_log_f32_e32 v188, v188
	v_log_f32_e32 v189, v189
	v_log_f32_e32 v190, v190
	v_log_f32_e32 v191, v191
	v_pk_mul_f32 v[220:221], v[230:231], v[184:185]
	v_pk_mul_f32 v[222:223], v[230:231], v[186:187]
	v_pk_mul_f32 v[224:225], v[230:231], v[188:189]
	v_pk_mul_f32 v[226:227], v[230:231], v[190:191]
	v_pk_fma_f32 v[220:221], v[184:185], v[230:231], v[220:221] neg_lo:[0,0,1] neg_hi:[0,0,1]
	v_pk_fma_f32 v[222:223], v[186:187], v[230:231], v[222:223] neg_lo:[0,0,1] neg_hi:[0,0,1]
	v_pk_fma_f32 v[224:225], v[188:189], v[230:231], v[224:225] neg_lo:[0,0,1] neg_hi:[0,0,1]
	v_pk_fma_f32 v[226:227], v[190:191], v[230:231], v[226:227] neg_lo:[0,0,1] neg_hi:[0,0,1]
	v_pk_fma_f32 v[220:221], v[232:233], v[184:185], v[220:221]
	v_pk_fma_f32 v[222:223], v[232:233], v[186:187], v[222:223]
	v_pk_fma_f32 v[224:225], v[232:233], v[188:189], v[224:225]
	v_pk_fma_f32 v[226:227], v[232:233], v[190:191], v[226:227]
	v_pk_fma_f32 v[220:221], v[230:231], v[184:185], v[220:221]
	v_pk_fma_f32 v[222:223], v[230:231], v[186:187], v[222:223]
	v_pk_fma_f32 v[224:225], v[230:231], v[188:189], v[224:225]
	v_pk_fma_f32 v[226:227], v[230:231], v[190:191], v[226:227]
	v_pk_add_f32 v[24:25], v[24:25], v[220:221] neg_lo:[0,1] neg_hi:[0,1]
	v_pk_add_f32 v[26:27], v[26:27], v[222:223] neg_lo:[0,1] neg_hi:[0,1]
	v_pk_add_f32 v[20:21], v[20:21], v[224:225] neg_lo:[0,1] neg_hi:[0,1]
	v_pk_add_f32 v[22:23], v[22:23], v[226:227] neg_lo:[0,1] neg_hi:[0,1]
	v_pk_mul_f32 v[24:25], v[234:235], v[24:25]
	v_pk_mul_f32 v[26:27], v[234:235], v[26:27]
	v_pk_mul_f32 v[20:21], v[234:235], v[20:21]
	v_pk_mul_f32 v[22:23], v[234:235], v[22:23]
	v_cvt_pk_bf16_f32 v30, v24, v25
	v_cvt_pk_bf16_f32 v31, v26, v27
	v_cvt_pk_bf16_f32 v32, v20, v21
	v_cvt_pk_bf16_f32 v33, v22, v23
	v_lshl_add_u64 v[28:29], s[16:17], 0, v[44:45]
	v_lshl_add_u64 v[28:29], v[150:151], 1, v[28:29]
	global_store_dwordx4 v[28:29], v[30:33], off offset:256
	s_mov_b64 s[10:11], 0

.LBB0_344:
	ds_read_b32 v30, v176 offset:704
	v_add_u32_e32 v32, 0xb0, v152
	v_ashrrev_i32_e32 v33, 31, v32
	v_lshlrev_b64 v[28:29], 9, v[32:33]
	s_mov_b64 s[36:37], -1
	s_waitcnt lgkmcnt(0)
	v_pk_mul_f32 v[18:19], v[18:19], v[30:31] op_sel_hi:[1,0]
	v_pk_mul_f32 v[16:17], v[16:17], v[30:31] op_sel_hi:[1,0]
	v_pk_mul_f32 v[14:15], v[14:15], v[30:31] op_sel_hi:[1,0]
	v_pk_mul_f32 v[12:13], v[12:13], v[30:31] op_sel_hi:[1,0]
	s_mov_b64 s[34:35], 0
	s_cmp_lt_i32 s54, 9
	s_mov_b64 s[10:11], 0
	s_cbranch_scc1 .LBB0_350
	s_cmp_eq_u32 s54, 9
	s_mov_b64 s[10:11], -1
	s_cbranch_scc0 .LBB0_347
	v_pk_add_f32 v[16:17], v[16:17], v[192:193]
	v_pk_add_f32 v[18:19], v[18:19], v[194:195]
	v_pk_add_f32 v[12:13], v[12:13], v[196:197]
	v_pk_add_f32 v[14:15], v[14:15], v[198:199]
	v_mul_f32_e64 v184, |v16|, s23
	v_mul_f32_e64 v185, |v17|, s23
	v_mul_f32_e64 v186, |v18|, s23
	v_mul_f32_e64 v187, |v19|, s23
	v_mul_f32_e64 v188, |v12|, s23
	v_mul_f32_e64 v189, |v13|, s23
	v_mul_f32_e64 v190, |v14|, s23
	v_mul_f32_e64 v191, |v15|, s23
	v_min_f32_e32 v16, 0, v16
	v_min_f32_e32 v17, 0, v17
	v_min_f32_e32 v18, 0, v18
	v_min_f32_e32 v19, 0, v19
	v_min_f32_e32 v12, 0, v12
	v_min_f32_e32 v13, 0, v13
	v_min_f32_e32 v14, 0, v14
	v_min_f32_e32 v15, 0, v15
	v_exp_f32_e32 v184, v184
	v_exp_f32_e32 v185, v185
	v_exp_f32_e32 v186, v186
	v_exp_f32_e32 v187, v187
	v_exp_f32_e32 v188, v188
	v_exp_f32_e32 v189, v189
	v_exp_f32_e32 v190, v190
	v_exp_f32_e32 v191, v191
	v_pk_add_f32 v[184:185], v[184:185], v[228:229]
	v_pk_add_f32 v[186:187], v[186:187], v[228:229]
	v_pk_add_f32 v[188:189], v[188:189], v[228:229]
	v_pk_add_f32 v[190:191], v[190:191], v[228:229]
	v_log_f32_e32 v184, v184
	v_log_f32_e32 v185, v185
	v_log_f32_e32 v186, v186
	v_log_f32_e32 v187, v187
	v_log_f32_e32 v188, v188
	v_log_f32_e32 v189, v189
	v_log_f32_e32 v190, v190
	v_log_f32_e32 v191, v191
	v_pk_mul_f32 v[220:221], v[230:231], v[184:185]
	v_pk_mul_f32 v[222:223], v[230:231], v[186:187]
	v_pk_mul_f32 v[224:225], v[230:231], v[188:189]
	v_pk_mul_f32 v[226:227], v[230:231], v[190:191]
	v_pk_fma_f32 v[220:221], v[184:185], v[230:231], v[220:221] neg_lo:[0,0,1] neg_hi:[0,0,1]
	v_pk_fma_f32 v[222:223], v[186:187], v[230:231], v[222:223] neg_lo:[0,0,1] neg_hi:[0,0,1]
	v_pk_fma_f32 v[224:225], v[188:189], v[230:231], v[224:225] neg_lo:[0,0,1] neg_hi:[0,0,1]
	v_pk_fma_f32 v[226:227], v[190:191], v[230:231], v[226:227] neg_lo:[0,0,1] neg_hi:[0,0,1]
	v_pk_fma_f32 v[220:221], v[232:233], v[184:185], v[220:221]
	v_pk_fma_f32 v[222:223], v[232:233], v[186:187], v[222:223]
	v_pk_fma_f32 v[224:225], v[232:233], v[188:189], v[224:225]
	v_pk_fma_f32 v[226:227], v[232:233], v[190:191], v[226:227]
	v_pk_fma_f32 v[220:221], v[230:231], v[184:185], v[220:221]
	v_pk_fma_f32 v[222:223], v[230:231], v[186:187], v[222:223]
	v_pk_fma_f32 v[224:225], v[230:231], v[188:189], v[224:225]
	v_pk_fma_f32 v[226:227], v[230:231], v[190:191], v[226:227]
	v_pk_add_f32 v[16:17], v[16:17], v[220:221] neg_lo:[0,1] neg_hi:[0,1]
	v_pk_add_f32 v[18:19], v[18:19], v[222:223] neg_lo:[0,1] neg_hi:[0,1]
	v_pk_add_f32 v[12:13], v[12:13], v[224:225] neg_lo:[0,1] neg_hi:[0,1]
	v_pk_add_f32 v[14:15], v[14:15], v[226:227] neg_lo:[0,1] neg_hi:[0,1]
	v_pk_mul_f32 v[16:17], v[234:235], v[16:17]
	v_pk_mul_f32 v[18:19], v[234:235], v[18:19]
	v_pk_mul_f32 v[12:13], v[234:235], v[12:13]
	v_pk_mul_f32 v[14:15], v[234:235], v[14:15]
	v_cvt_pk_bf16_f32 v22, v16, v17
	v_cvt_pk_bf16_f32 v23, v18, v19
	v_cvt_pk_bf16_f32 v24, v12, v13
	v_cvt_pk_bf16_f32 v25, v14, v15
	v_lshl_add_u64 v[20:21], s[16:17], 0, v[28:29]
	v_lshl_add_u64 v[20:21], v[150:151], 1, v[20:21]
	global_store_dwordx4 v[20:21], v[22:25], off
	s_mov_b64 s[10:11], 0

.LBB0_360:
	v_mov_b32_e32 v31, v30
	s_nop 0
	v_mov_b32_e32 v12, v30
	v_mov_b32_e32 v13, v30
	v_pk_mul_f32 v[10:11], v[10:11], v[12:13]
	v_pk_mul_f32 v[8:9], v[8:9], v[30:31]
	v_pk_mul_f32 v[6:7], v[6:7], v[12:13]
	v_pk_mul_f32 v[4:5], v[4:5], v[30:31]
	s_mov_b64 s[34:35], -1
	s_mov_b64 s[30:31], 0
	s_cmp_lt_i32 s54, 9
	s_mov_b64 s[10:11], 0
	s_cbranch_scc1 .LBB0_364
	s_cmp_eq_u32 s54, 9
	s_mov_b64 s[10:11], -1
	s_cbranch_scc0 .LBB0_363
	v_pk_add_f32 v[8:9], v[8:9], v[200:201]
	v_pk_add_f32 v[10:11], v[10:11], v[202:203]
	v_pk_add_f32 v[4:5], v[4:5], v[204:205]
	v_pk_add_f32 v[6:7], v[6:7], v[206:207]
	v_mul_f32_e64 v184, |v8|, s23
	v_mul_f32_e64 v185, |v9|, s23
	v_mul_f32_e64 v186, |v10|, s23
	v_mul_f32_e64 v187, |v11|, s23
	v_mul_f32_e64 v188, |v4|, s23
	v_mul_f32_e64 v189, |v5|, s23
	v_mul_f32_e64 v190, |v6|, s23
	v_mul_f32_e64 v191, |v7|, s23
	v_min_f32_e32 v8, 0, v8
	v_min_f32_e32 v9, 0, v9
	v_min_f32_e32 v10, 0, v10
	v_min_f32_e32 v11, 0, v11
	v_min_f32_e32 v4, 0, v4
	v_min_f32_e32 v5, 0, v5
	v_min_f32_e32 v6, 0, v6
	v_min_f32_e32 v7, 0, v7
	v_exp_f32_e32 v184, v184
	v_exp_f32_e32 v185, v185
	v_exp_f32_e32 v186, v186
	v_exp_f32_e32 v187, v187
	v_exp_f32_e32 v188, v188
	v_exp_f32_e32 v189, v189
	v_exp_f32_e32 v190, v190
	v_exp_f32_e32 v191, v191
	v_pk_add_f32 v[184:185], v[184:185], v[228:229]
	v_pk_add_f32 v[186:187], v[186:187], v[228:229]
	v_pk_add_f32 v[188:189], v[188:189], v[228:229]
	v_pk_add_f32 v[190:191], v[190:191], v[228:229]
	v_log_f32_e32 v184, v184
	v_log_f32_e32 v185, v185
	v_log_f32_e32 v186, v186
	v_log_f32_e32 v187, v187
	v_log_f32_e32 v188, v188
	v_log_f32_e32 v189, v189
	v_log_f32_e32 v190, v190
	v_log_f32_e32 v191, v191
	v_pk_mul_f32 v[220:221], v[230:231], v[184:185]
	v_pk_mul_f32 v[222:223], v[230:231], v[186:187]
	v_pk_mul_f32 v[224:225], v[230:231], v[188:189]
	v_pk_mul_f32 v[226:227], v[230:231], v[190:191]
	v_pk_fma_f32 v[220:221], v[184:185], v[230:231], v[220:221] neg_lo:[0,0,1] neg_hi:[0,0,1]
	v_pk_fma_f32 v[222:223], v[186:187], v[230:231], v[222:223] neg_lo:[0,0,1] neg_hi:[0,0,1]
	v_pk_fma_f32 v[224:225], v[188:189], v[230:231], v[224:225] neg_lo:[0,0,1] neg_hi:[0,0,1]
	v_pk_fma_f32 v[226:227], v[190:191], v[230:231], v[226:227] neg_lo:[0,0,1] neg_hi:[0,0,1]
	v_pk_fma_f32 v[220:221], v[232:233], v[184:185], v[220:221]
	v_pk_fma_f32 v[222:223], v[232:233], v[186:187], v[222:223]
	v_pk_fma_f32 v[224:225], v[232:233], v[188:189], v[224:225]
	v_pk_fma_f32 v[226:227], v[232:233], v[190:191], v[226:227]
	v_pk_fma_f32 v[220:221], v[230:231], v[184:185], v[220:221]
	v_pk_fma_f32 v[222:223], v[230:231], v[186:187], v[222:223]
	v_pk_fma_f32 v[224:225], v[230:231], v[188:189], v[224:225]
	v_pk_fma_f32 v[226:227], v[230:231], v[190:191], v[226:227]
	v_pk_add_f32 v[8:9], v[8:9], v[220:221] neg_lo:[0,1] neg_hi:[0,1]
	v_pk_add_f32 v[10:11], v[10:11], v[222:223] neg_lo:[0,1] neg_hi:[0,1]
	v_pk_add_f32 v[4:5], v[4:5], v[224:225] neg_lo:[0,1] neg_hi:[0,1]
	v_pk_add_f32 v[6:7], v[6:7], v[226:227] neg_lo:[0,1] neg_hi:[0,1]
	v_pk_mul_f32 v[8:9], v[234:235], v[8:9]
	v_pk_mul_f32 v[10:11], v[234:235], v[10:11]
	v_pk_mul_f32 v[4:5], v[234:235], v[4:5]
	v_pk_mul_f32 v[6:7], v[234:235], v[6:7]
	v_cvt_pk_bf16_f32 v14, v8, v9
	v_cvt_pk_bf16_f32 v15, v10, v11
	v_cvt_pk_bf16_f32 v16, v4, v5
	v_cvt_pk_bf16_f32 v17, v6, v7
	v_lshl_add_u64 v[12:13], s[16:17], 0, v[28:29]
	v_lshl_add_u64 v[12:13], v[150:151], 1, v[12:13]
	global_store_dwordx4 v[12:13], v[14:17], off offset:256
	s_mov_b64 s[10:11], 0
